# K1 W_in transpose: two 16-row steps (32 loads) per drain
# speedup vs baseline: 1.0020x; 1.0006x over previous
.LBB0_34:
	v_mov_b32_e32 v100, 0
	v_mov_b32_e32 v101, 0
	v_mov_b32_e32 v102, 0
	v_mov_b32_e32 v103, 0
	v_mov_b32_e32 v104, 0
	v_mov_b32_e32 v105, 0
	v_mov_b32_e32 v106, 0
	v_mov_b32_e32 v107, 0
	v_mov_b32_e32 v108, 0
	v_mov_b32_e32 v109, 0
	v_mov_b32_e32 v110, 0
	v_mov_b32_e32 v111, 0
	v_mov_b32_e32 v112, 0
	v_mov_b32_e32 v113, 0
	v_mov_b32_e32 v114, 0
	v_mov_b32_e32 v115, 0
	s_add_u32 s24, s22, 0x7c300
	s_addc_u32 s25, s23, 0
	s_and_saveexec_b64 s[6:7], s[18:19]
	s_cbranch_execz .Lk1_skipw
	v_lshl_add_u64 v[116:117], v[34:35], 0, s[22:23]
	global_load_dword v100, v[116:117], off
	v_lshl_add_u64 v[118:119], v[30:31], 0, s[22:23]
	global_load_dword v101, v[118:119], off
	v_lshl_add_u64 v[116:117], v[28:29], 0, s[22:23]
	global_load_dword v102, v[116:117], off
	v_lshl_add_u64 v[118:119], v[26:27], 0, s[22:23]
	global_load_dword v103, v[118:119], off
	v_lshl_add_u64 v[116:117], v[24:25], 0, s[22:23]
	global_load_dword v104, v[116:117], off
	v_lshl_add_u64 v[118:119], v[22:23], 0, s[22:23]
	global_load_dword v105, v[118:119], off
	v_lshl_add_u64 v[116:117], v[20:21], 0, s[22:23]
	global_load_dword v106, v[116:117], off
	v_lshl_add_u64 v[118:119], v[16:17], 0, s[22:23]
	global_load_dword v107, v[118:119], off
	v_lshl_add_u64 v[116:117], v[34:35], 0, s[24:25]
	global_load_dword v108, v[116:117], off
	v_lshl_add_u64 v[118:119], v[30:31], 0, s[24:25]
	global_load_dword v109, v[118:119], off
	v_lshl_add_u64 v[116:117], v[28:29], 0, s[24:25]
	global_load_dword v110, v[116:117], off
	v_lshl_add_u64 v[118:119], v[26:27], 0, s[24:25]
	global_load_dword v111, v[118:119], off
	v_lshl_add_u64 v[116:117], v[24:25], 0, s[24:25]
	global_load_dword v112, v[116:117], off
	v_lshl_add_u64 v[118:119], v[22:23], 0, s[24:25]
	global_load_dword v113, v[118:119], off
	v_lshl_add_u64 v[116:117], v[20:21], 0, s[24:25]
	global_load_dword v114, v[116:117], off
	v_lshl_add_u64 v[118:119], v[16:17], 0, s[24:25]
	global_load_dword v115, v[118:119], off
.Lk1_skipw:
	s_or_b64 exec, exec, s[6:7]
	s_andn2_b64 vcc, exec, s[12:13]
	s_cbranch_vccnz .Lk1_nokscale
	v_lshl_add_u64 v[116:117], v[32:33], 0, s[20:21]
	v_lshl_add_u64 v[118:119], v[18:19], 0, s[20:21]
	global_load_dword v120, v[116:117], off
	global_load_dword v121, v[118:119], off offset:8
	global_load_dword v122, v[118:119], off offset:16
	global_load_dword v123, v[118:119], off offset:24
	global_load_dword v124, v[118:119], off offset:32
	global_load_dword v125, v[118:119], off offset:40
	global_load_dword v126, v[118:119], off offset:48
	global_load_dword v127, v[118:119], off offset:56
	global_load_dword v128, v[116:117], off offset:64
	global_load_dword v129, v[118:119], off offset:72
	global_load_dword v130, v[118:119], off offset:80
	global_load_dword v131, v[118:119], off offset:88
	global_load_dword v132, v[118:119], off offset:96
	global_load_dword v133, v[118:119], off offset:104
	global_load_dword v134, v[118:119], off offset:112
	global_load_dword v135, v[118:119], off offset:120
	s_waitcnt vmcnt(0)
	v_mul_f32_e32 v100, v100, v120
	v_mul_f32_e32 v101, v101, v121
	v_mul_f32_e32 v102, v102, v122
	v_mul_f32_e32 v103, v103, v123
	v_mul_f32_e32 v104, v104, v124
	v_mul_f32_e32 v105, v105, v125
	v_mul_f32_e32 v106, v106, v126
	v_mul_f32_e32 v107, v107, v127
	v_mul_f32_e32 v108, v108, v128
	v_mul_f32_e32 v109, v109, v129
	v_mul_f32_e32 v110, v110, v130
	v_mul_f32_e32 v111, v111, v131
	v_mul_f32_e32 v112, v112, v132
	v_mul_f32_e32 v113, v113, v133
	v_mul_f32_e32 v114, v114, v134
	v_mul_f32_e32 v115, v115, v135
.Lk1_nokscale:
	s_waitcnt vmcnt(0)
	ds_write_b32 v6, v100
	ds_write_b32 v6, v101 offset:264
	ds_write_b32 v6, v102 offset:528
	ds_write_b32 v6, v103 offset:792
	ds_write_b32 v6, v104 offset:1056
	ds_write_b32 v6, v105 offset:1320
	ds_write_b32 v6, v106 offset:1584
	ds_write_b32 v6, v107 offset:1848
	ds_write_b32 v6, v108 offset:2112
	ds_write_b32 v6, v109 offset:2376
	ds_write_b32 v6, v110 offset:2640
	ds_write_b32 v6, v111 offset:2904
	ds_write_b32 v6, v112 offset:3168
	ds_write_b32 v6, v113 offset:3432
	ds_write_b32 v6, v114 offset:3696
	ds_write_b32 v6, v115 offset:3960
	s_add_u32 s22, s22, 0xf8600
	s_addc_u32 s23, s23, 0
	v_add_u32_e32 v6, 0x1080, v6
	v_lshl_add_u64 v[18:19], v[18:19], 0, 64
	v_lshl_add_u64 v[18:19], v[18:19], 0, 64
	v_lshl_add_u64 v[32:33], v[32:33], 0, 64
	v_lshl_add_u64 v[32:33], v[32:33], 0, 64
	s_cmp_lg_u32 s22, 0x1f0c00
	s_cbranch_scc1 .LBB0_34
	s_branch .LBB0_7
